# RG-LRU finalize items handed out longest-carry first (pop index k -> b=k&7, j=63-(k>>3)) so the phase tail gets the short items
# baseline (speedup 1.0000x reference)
; DEV int opaque_tid() { int t = (int)threadIdx.x; asm volatile("" : "+v"(t)); return t; }
; __device__ void lru_final_item(const Params& P, int l, int item) {
;   const int tid = opaque_tid(), lane = tid & 63, w = tid >> 6;
;   const int j = item & 63, b = item >> 6;
;   float carry[8];
; #pragma unroll
;   for (int k = 0; k < 8; ++k) carry[k] = 0.f;
;   for (int jj = 0; jj < j; ++jj) {
;     const float* ap = P.AP + (size_t)(b * 64 + jj) * 512 + lane * 8;
;     const float* he = P.HE + (size_t)(b * 64 + jj) * 512 + lane * 8;
;     const float4 a0 = *(const float4*)ap, a1 = *(const float4*)(ap + 4);
;     const float4 h0 = *(const float4*)he, h1 = *(const float4*)(he + 4);
;     carry[0] = a0.x * carry[0] + h0.x; carry[1] = a0.y * carry[1] + h0.y; carry[2] = a0.z * carry[2] + h0.z; carry[3] = a0.w * carry[3] + h0.w;
;     carry[4] = a1.x * carry[4] + h1.x; carry[5] = a1.y * carry[5] + h1.y; carry[6] = a1.z * carry[6] + h1.z; carry[7] = a1.w * carry[7] + h1.w;
;   }
; __device__ void run_phase(const Params& P, int ph, char* smem, bool do_store) {
;     ...
;         for (;;) {
;           __syncthreads();
;           if (opaque_tid() == 0) *slot = __hip_atomic_fetch_add(&qh[32], 1u, __ATOMIC_RELAXED, __HIP_MEMORY_SCOPE_AGENT);
;           __syncthreads();
;           const unsigned k = *slot;
;           if (k >= 512u) break;
;           lru_final_item(P, l, (int)k);
.LBB0_211:
	s_or_b64 exec, exec, s[0:1]
	s_waitcnt lgkmcnt(0)
	s_barrier
	ds_read_b32 v0, v204
	s_movk_i32 s0, 0x1ff
	s_waitcnt lgkmcnt(0)
	v_cmp_lt_u32_e32 vcc, s0, v0
	v_readfirstlane_b32 s2, v0
	s_mov_b64 s[0:1], -1
	s_cbranch_vccnz .LBB0_206
	v_mov_b32_e32 v16, v202
	s_lshr_b32 s0, s2, 3
	s_sub_i32 s0, 63, s0
	s_and_b32 s2, s2, 7
	s_lshl_b32 s2, s2, 6
	s_or_b32 s2, s2, s0
	s_and_b32 s0, s2, 63
	v_and_b32_e32 v0, 63, v16
	s_cmp_lg_u32 s0, 0
	v_lshlrev_b32_e32 v176, 3, v0
	s_cbranch_scc0 .LBB0_220
	s_lshl_b32 s4, s0, 11
	s_lshl_b32 s0, s2, 11
	s_and_b32 s0, s0, 0xe0000
	v_readlane_b32 s40, v251, 42
	v_lshl_or_b32 v2, v0, 5, s0
	v_mov_b32_e32 v3, v177
	v_readlane_b32 s52, v251, 54
	v_readlane_b32 s53, v251, 55
	v_readlane_b32 s54, v251, 56
	v_readlane_b32 s55, v251, 57
	v_mov_b32_e32 v8, 0
	s_mov_b64 s[0:1], 0
	v_lshl_add_u64 v[0:1], s[54:55], 0, v[2:3]
	v_lshl_add_u64 v[2:3], s[52:53], 0, v[2:3]
	v_mov_b32_e32 v9, v8
	v_mov_b32_e32 v10, v8
	v_mov_b32_e32 v11, v8
	v_mov_b32_e32 v12, v8
	v_mov_b32_e32 v13, v8
	v_mov_b32_e32 v14, v8
	v_mov_b32_e32 v15, v8
	v_readlane_b32 s41, v251, 43
	v_readlane_b32 s42, v251, 44
	v_readlane_b32 s43, v251, 45
	v_readlane_b32 s44, v251, 46
	v_readlane_b32 s45, v251, 47
	v_readlane_b32 s46, v251, 48
	v_readlane_b32 s47, v251, 49
	v_readlane_b32 s48, v251, 50
	v_readlane_b32 s49, v251, 51
	v_readlane_b32 s50, v251, 52
	v_readlane_b32 s51, v251, 53
